# adds attention row-max on raw scores (one scale multiply after the max3 chain instead of 32 per tile, bit-identical)
# baseline (speedup 1.0000x reference)
.LBB0_1082:
	s_or_b64 exec, exec, s[70:71]
	ds_read_b128 v[66:69], v220
	ds_read_b128 v[82:85], v220 offset:32
	ds_read_b128 v[86:89], v220 offset:64
	ds_read_b128 v[90:93], v220 offset:96
	s_waitcnt lgkmcnt(3)
	v_mfma_f32_32x32x16_bf16 v[66:81], v[66:69], v[98:101], 0
	ds_read_b128 v[94:97], v220 offset:128
	s_waitcnt lgkmcnt(3)
	v_mfma_f32_32x32x16_bf16 v[66:81], v[82:85], v[102:105], v[66:81]
	ds_read_b128 v[82:85], v220 offset:160
	s_waitcnt lgkmcnt(3)
	v_mfma_f32_32x32x16_bf16 v[66:81], v[86:89], v[106:109], v[66:81]
	ds_read_b128 v[86:89], v220 offset:192
	s_waitcnt lgkmcnt(3)
	v_mfma_f32_32x32x16_bf16 v[66:81], v[90:93], v[110:113], v[66:81]
	ds_read_b128 v[90:93], v220 offset:224
	s_waitcnt lgkmcnt(3)
	v_mfma_f32_32x32x16_bf16 v[66:81], v[94:97], v[114:117], v[66:81]
	ds_read_b128 v[94:97], v220 offset:256
	s_waitcnt lgkmcnt(3)
	v_mfma_f32_32x32x16_bf16 v[66:81], v[82:85], v[118:121], v[66:81]
	ds_read_b128 v[82:85], v220 offset:288
	s_waitcnt lgkmcnt(3)
	v_mfma_f32_32x32x16_bf16 v[66:81], v[86:89], v[122:125], v[66:81]
	ds_read_b128 v[86:89], v220 offset:320
	s_waitcnt lgkmcnt(3)
	v_mfma_f32_32x32x16_bf16 v[66:81], v[90:93], v[126:129], v[66:81]
	ds_read_b128 v[90:93], v220 offset:352
	s_waitcnt lgkmcnt(3)
	v_mfma_f32_32x32x16_bf16 v[66:81], v[94:97], v[130:133], v[66:81]
	ds_read_b128 v[94:97], v220 offset:12800
	s_waitcnt lgkmcnt(3)
	v_mfma_f32_32x32x16_bf16 v[66:81], v[82:85], v[134:137], v[66:81]
	ds_read_b128 v[226:229], v220 offset:12832
	s_waitcnt lgkmcnt(3)
	v_mfma_f32_32x32x16_bf16 v[66:81], v[86:89], v[138:141], v[66:81]
	ds_read_b128 v[230:233], v220 offset:12864
	s_waitcnt lgkmcnt(3)
	v_mfma_f32_32x32x16_bf16 v[66:81], v[90:93], v[142:145], v[66:81]
	ds_read_b128 v[234:237], v220 offset:12896
	s_waitcnt lgkmcnt(3)
	v_mfma_f32_32x32x16_bf16 v[82:97], v[94:97], v[98:101], 0
	ds_read_b128 v[238:241], v220 offset:12928
	s_waitcnt lgkmcnt(3)
	v_mfma_f32_32x32x16_bf16 v[82:97], v[226:229], v[102:105], v[82:97]
	ds_read_b128 v[226:229], v220 offset:12960
	s_waitcnt lgkmcnt(3)
	v_mfma_f32_32x32x16_bf16 v[82:97], v[230:233], v[106:109], v[82:97]
	ds_read_b128 v[230:233], v220 offset:12992
	s_waitcnt lgkmcnt(3)
	v_mfma_f32_32x32x16_bf16 v[82:97], v[234:237], v[110:113], v[82:97]
	ds_read_b128 v[234:237], v220 offset:13024
	s_waitcnt lgkmcnt(3)
	v_mfma_f32_32x32x16_bf16 v[82:97], v[238:241], v[114:117], v[82:97]
	ds_read_b128 v[238:241], v220 offset:13056
	s_waitcnt lgkmcnt(3)
	v_mfma_f32_32x32x16_bf16 v[82:97], v[226:229], v[118:121], v[82:97]
	ds_read_b128 v[226:229], v220 offset:13088
	s_waitcnt lgkmcnt(3)
	v_mfma_f32_32x32x16_bf16 v[82:97], v[230:233], v[122:125], v[82:97]
	ds_read_b128 v[230:233], v220 offset:13120
	s_waitcnt lgkmcnt(3)
	v_mfma_f32_32x32x16_bf16 v[82:97], v[234:237], v[126:129], v[82:97]
	ds_read_b128 v[234:237], v220 offset:13152
	s_waitcnt lgkmcnt(3)
	v_mfma_f32_32x32x16_bf16 v[82:97], v[238:241], v[130:133], v[82:97]
	s_waitcnt lgkmcnt(2)
	v_mfma_f32_32x32x16_bf16 v[82:97], v[226:229], v[134:137], v[82:97]
	s_waitcnt lgkmcnt(1)
	v_mfma_f32_32x32x16_bf16 v[82:97], v[230:233], v[138:141], v[82:97]
	s_waitcnt lgkmcnt(0)
	v_mfma_f32_32x32x16_bf16 v[82:97], v[234:237], v[142:145], v[82:97]
	s_mov_b32 s10, 0xf149f2ca
	s_nop 5
	v_max3_f32 v0, v66, v67, v68
	v_max3_f32 v0, v0, v69, v70
	v_max3_f32 v0, v0, v71, v72
	v_max3_f32 v0, v0, v73, v74
	v_max3_f32 v0, v0, v75, v76
	v_max3_f32 v0, v0, v77, v78
	v_max3_f32 v0, v0, v79, v80
	v_max3_f32 v0, v0, v81, v82
	v_max3_f32 v0, v0, v83, v84
	v_max3_f32 v0, v0, v85, v86
	v_max3_f32 v0, v0, v87, v88
	v_max3_f32 v0, v0, v89, v90
	v_max3_f32 v0, v0, v91, v92
	v_max3_f32 v0, v0, v93, v94
	v_max3_f32 v0, v0, v95, v96
	v_max_f32_e32 v0, v0, v97
	v_mul_f32_e32 v0, 0x3dd53b94, v0
	v_max_f32_e32 v0, s10, v0
	ds_bpermute_b32 v208, v219, v0
	v_add_u32_e32 v243, 0x6000, v221
	v_add_u32_e32 v244, 0x7000, v221
	v_add_u32_e32 v245, 0x8000, v221
	s_waitcnt lgkmcnt(0)
	v_max3_f32 v226, v225, v0, v208
	v_fma_f32 v66, v66, s58, -v226
	v_exp_f32_e32 v208, v66
	v_fma_f32 v66, v67, s58, -v226
	v_exp_f32_e32 v67, v66
	v_fma_f32 v66, v68, s58, -v226
	v_exp_f32_e32 v209, v66
	v_fma_f32 v66, v69, s58, -v226
	v_exp_f32_e32 v210, v66
	v_fma_f32 v68, v70, s58, -v226
	v_add_f32_e32 v66, 0, v208
	v_exp_f32_e32 v211, v68
	v_fma_f32 v68, v71, s58, -v226
	v_sub_f32_e32 v0, v225, v226
	v_add_f32_e32 v66, v67, v66
	v_exp_f32_e32 v225, v68
	v_fma_f32 v68, v72, s58, -v226
	v_add_f32_e32 v66, v209, v66
	v_exp_f32_e32 v227, v68
	v_fma_f32 v68, v73, s58, -v226
	v_add_f32_e32 v66, v210, v66
	v_exp_f32_e32 v228, v68
	v_fma_f32 v68, v74, s58, -v226
	v_add_f32_e32 v66, v211, v66
	v_exp_f32_e32 v229, v68
	v_fma_f32 v68, v75, s58, -v226
	v_add_f32_e32 v66, v225, v66
	v_exp_f32_e32 v230, v68
	v_fma_f32 v68, v76, s58, -v226
	v_add_f32_e32 v66, v227, v66
	v_exp_f32_e32 v231, v68
	v_fma_f32 v68, v77, s58, -v226
	v_add_f32_e32 v66, v228, v66
	v_exp_f32_e32 v232, v68
	v_fma_f32 v68, v78, s58, -v226
	v_add_f32_e32 v66, v229, v66
	v_exp_f32_e32 v233, v68
	v_fma_f32 v68, v79, s58, -v226
	v_add_f32_e32 v66, v230, v66
	v_exp_f32_e32 v234, v68
	v_fma_f32 v68, v80, s58, -v226
	v_add_f32_e32 v66, v231, v66
	v_exp_f32_e32 v235, v68
	v_fma_f32 v68, v81, s58, -v226
	v_add_f32_e32 v66, v232, v66
	v_exp_f32_e32 v236, v68
	v_fma_f32 v68, v82, s58, -v226
	v_add_f32_e32 v66, v233, v66
	v_exp_f32_e32 v237, v68
	v_fma_f32 v68, v83, s58, -v226
	v_add_f32_e32 v66, v234, v66
	v_exp_f32_e32 v238, v68
	v_fma_f32 v68, v84, s58, -v226
	v_add_f32_e32 v66, v235, v66
	v_exp_f32_e32 v239, v68
	v_fma_f32 v68, v85, s58, -v226
	v_add_f32_e32 v66, v236, v66
	v_exp_f32_e32 v240, v68
	v_fma_f32 v68, v86, s58, -v226
	v_exp_f32_e32 v241, v68
	v_fma_f32 v68, v87, s58, -v226
	v_add_f32_e32 v66, v237, v66
	v_exp_f32_e32 v242, v68
	v_fma_f32 v68, v88, s58, -v226
	v_add_f32_e32 v66, v238, v66
	v_exp_f32_e32 v88, v68
	v_fma_f32 v68, v89, s58, -v226
	v_add_f32_e32 v66, v239, v66
	v_exp_f32_e32 v89, v68
	v_fma_f32 v68, v90, s58, -v226
	v_add_f32_e32 v66, v240, v66
	v_exp_f32_e32 v90, v68
	v_fma_f32 v68, v91, s58, -v226
	v_add_f32_e32 v66, v241, v66
	v_exp_f32_e32 v91, v68
	v_fma_f32 v68, v92, s58, -v226
	v_add_f32_e32 v66, v242, v66
	v_exp_f32_e32 v92, v68
	v_fma_f32 v68, v93, s58, -v226
	v_add_f32_e32 v66, v88, v66
	v_exp_f32_e32 v93, v68
	v_fma_f32 v68, v94, s58, -v226
	v_add_f32_e32 v66, v89, v66
	v_exp_f32_e32 v94, v68
	v_fma_f32 v68, v95, s58, -v226
	v_add_f32_e32 v66, v90, v66
	v_exp_f32_e32 v95, v68
	v_fma_f32 v68, v96, s58, -v226
	v_add_f32_e32 v66, v91, v66
	v_exp_f32_e32 v96, v68
	v_fma_f32 v68, v97, s58, -v226
	v_add_f32_e32 v66, v92, v66
	v_exp_f32_e32 v0, v0
	v_exp_f32_e32 v97, v68
	v_add_f32_e32 v66, v93, v66
	v_add_f32_e32 v66, v94, v66
	ds_read2_b64 v[68:71], v243 offset0:128 offset1:130
	ds_read2_b64 v[72:75], v244 offset0:160 offset1:162
	ds_read2_b64 v[76:79], v245 offset0:192 offset1:194
	v_add_f32_e32 v66, v95, v66
	v_add_f32_e32 v66, v96, v66
	v_pk_mul_f32 v[64:65], v[64:65], v[0:1] op_sel_hi:[1,0]
	v_pk_mul_f32 v[62:63], v[62:63], v[0:1] op_sel_hi:[1,0]
	v_pk_mul_f32 v[60:61], v[60:61], v[0:1] op_sel_hi:[1,0]
	v_pk_mul_f32 v[58:59], v[58:59], v[0:1] op_sel_hi:[1,0]
	v_pk_mul_f32 v[56:57], v[56:57], v[0:1] op_sel_hi:[1,0]
	v_pk_mul_f32 v[54:55], v[54:55], v[0:1] op_sel_hi:[1,0]
	v_pk_mul_f32 v[52:53], v[52:53], v[0:1] op_sel_hi:[1,0]
	v_pk_mul_f32 v[50:51], v[50:51], v[0:1] op_sel_hi:[1,0]
	v_pk_mul_f32 v[48:49], v[48:49], v[0:1] op_sel_hi:[1,0]
	v_pk_mul_f32 v[46:47], v[46:47], v[0:1] op_sel_hi:[1,0]
	v_pk_mul_f32 v[44:45], v[44:45], v[0:1] op_sel_hi:[1,0]
	v_pk_mul_f32 v[42:43], v[42:43], v[0:1] op_sel_hi:[1,0]
	v_pk_mul_f32 v[40:41], v[40:41], v[0:1] op_sel_hi:[1,0]
	v_pk_mul_f32 v[38:39], v[38:39], v[0:1] op_sel_hi:[1,0]
	v_pk_mul_f32 v[36:37], v[36:37], v[0:1] op_sel_hi:[1,0]
	v_pk_mul_f32 v[34:35], v[34:35], v[0:1] op_sel_hi:[1,0]
	v_pk_mul_f32 v[32:33], v[32:33], v[0:1] op_sel_hi:[1,0]
	v_pk_mul_f32 v[30:31], v[30:31], v[0:1] op_sel_hi:[1,0]
	v_pk_mul_f32 v[28:29], v[28:29], v[0:1] op_sel_hi:[1,0]
	v_pk_mul_f32 v[26:27], v[26:27], v[0:1] op_sel_hi:[1,0]
	v_pk_mul_f32 v[24:25], v[24:25], v[0:1] op_sel_hi:[1,0]
	v_pk_mul_f32 v[22:23], v[22:23], v[0:1] op_sel_hi:[1,0]
	v_pk_mul_f32 v[20:21], v[20:21], v[0:1] op_sel_hi:[1,0]
	v_pk_mul_f32 v[18:19], v[18:19], v[0:1] op_sel_hi:[1,0]
	v_pk_mul_f32 v[16:17], v[16:17], v[0:1] op_sel_hi:[1,0]
	v_pk_mul_f32 v[14:15], v[14:15], v[0:1] op_sel_hi:[1,0]
	v_pk_mul_f32 v[12:13], v[12:13], v[0:1] op_sel_hi:[1,0]
	v_pk_mul_f32 v[10:11], v[10:11], v[0:1] op_sel_hi:[1,0]
	v_pk_mul_f32 v[8:9], v[8:9], v[0:1] op_sel_hi:[1,0]
	v_pk_mul_f32 v[6:7], v[6:7], v[0:1] op_sel_hi:[1,0]
	v_pk_mul_f32 v[4:5], v[4:5], v[0:1] op_sel_hi:[1,0]
	v_pk_mul_f32 v[2:3], v[2:3], v[0:1] op_sel_hi:[1,0]
	v_add_f32_e32 v66, v97, v66
	v_cvt_pk_bf16_f32 v80, v208, v67
	v_cvt_pk_bf16_f32 v81, v209, v210
	v_cvt_pk_bf16_f32 v82, v211, v225
	v_cvt_pk_bf16_f32 v83, v227, v228
	v_add_u32_e32 v67, 0x9000, v221
	ds_read2_b64 v[84:87], v67 offset0:224 offset1:226
	s_waitcnt lgkmcnt(3)
	v_mfma_f32_32x32x16_bf16 v[50:65], v[68:71], v[80:83], v[50:65]
	ds_read2_b64 v[68:71], v243 offset0:132 offset1:134
	s_waitcnt lgkmcnt(3)
	v_mfma_f32_32x32x16_bf16 v[34:49], v[72:75], v[80:83], v[34:49]
	ds_read2_b64 v[72:75], v244 offset0:164 offset1:166
	s_waitcnt lgkmcnt(3)
	v_mfma_f32_32x32x16_bf16 v[18:33], v[76:79], v[80:83], v[18:33]
	ds_read2_b64 v[76:79], v245 offset0:196 offset1:198
	s_waitcnt lgkmcnt(3)
	v_mfma_f32_32x32x16_bf16 v[2:17], v[84:87], v[80:83], v[2:17]
	ds_read2_b64 v[80:83], v67 offset0:228 offset1:230
	v_cvt_pk_bf16_f32 v84, v229, v230
	v_cvt_pk_bf16_f32 v85, v231, v232
	v_cvt_pk_bf16_f32 v86, v233, v234
	v_cvt_pk_bf16_f32 v87, v235, v236
	s_waitcnt lgkmcnt(3)
	s_nop 0
	v_mfma_f32_32x32x16_bf16 v[50:65], v[68:71], v[84:87], v[50:65]
	ds_read2_b64 v[68:71], v243 offset0:136 offset1:138
	s_waitcnt lgkmcnt(3)
	v_mfma_f32_32x32x16_bf16 v[34:49], v[72:75], v[84:87], v[34:49]
	ds_read2_b64 v[72:75], v244 offset0:168 offset1:170
	s_waitcnt lgkmcnt(3)
	v_mfma_f32_32x32x16_bf16 v[18:33], v[76:79], v[84:87], v[18:33]
	ds_read2_b64 v[76:79], v245 offset0:200 offset1:202
	s_waitcnt lgkmcnt(3)
	v_mfma_f32_32x32x16_bf16 v[2:17], v[80:83], v[84:87], v[2:17]
	ds_read2_b64 v[80:83], v67 offset0:232 offset1:234
	v_cvt_pk_bf16_f32 v84, v237, v238
	v_cvt_pk_bf16_f32 v85, v239, v240
	v_cvt_pk_bf16_f32 v86, v241, v242
	v_cvt_pk_bf16_f32 v87, v88, v89
	s_waitcnt lgkmcnt(3)
	s_nop 0
	v_mfma_f32_32x32x16_bf16 v[50:65], v[68:71], v[84:87], v[50:65]
	ds_read2_b64 v[68:71], v243 offset0:140 offset1:142
	s_waitcnt lgkmcnt(3)
	v_mfma_f32_32x32x16_bf16 v[34:49], v[72:75], v[84:87], v[34:49]
	ds_read2_b64 v[72:75], v244 offset0:172 offset1:174
	s_waitcnt lgkmcnt(3)
	v_mfma_f32_32x32x16_bf16 v[18:33], v[76:79], v[84:87], v[18:33]
	ds_read2_b64 v[76:79], v245 offset0:204 offset1:206
	s_waitcnt lgkmcnt(3)
	v_mfma_f32_32x32x16_bf16 v[2:17], v[80:83], v[84:87], v[2:17]
	ds_read2_b64 v[80:83], v67 offset0:236 offset1:238
	v_cvt_pk_bf16_f32 v84, v90, v91
	v_cvt_pk_bf16_f32 v85, v92, v93
	v_cvt_pk_bf16_f32 v86, v94, v95
	v_cvt_pk_bf16_f32 v87, v96, v97
	s_waitcnt lgkmcnt(3)
	s_nop 0
	v_mfma_f32_32x32x16_bf16 v[50:65], v[68:71], v[84:87], v[50:65]
	s_waitcnt lgkmcnt(2)
	v_mfma_f32_32x32x16_bf16 v[34:49], v[72:75], v[84:87], v[34:49]
	s_waitcnt lgkmcnt(1)
	v_mfma_f32_32x32x16_bf16 v[18:33], v[76:79], v[84:87], v[18:33]
	s_waitcnt lgkmcnt(0)
	v_mfma_f32_32x32x16_bf16 v[2:17], v[80:83], v[84:87], v[2:17]
	s_add_i32 s9, s9, 64
	v_fmac_f32_e32 v66, v224, v0
	s_mov_b64 s[10:11], 0x80
	s_add_i32 s8, s8, 1
	v_cmp_eq_u32_e32 vcc, s9, v223
	v_lshl_add_u64 v[198:199], v[198:199], 0, s[10:11]
	s_or_b64 s[90:91], vcc, s[90:91]
	v_mov_b32_e32 v225, v226
	v_mov_b32_e32 v224, v66
	s_andn2_b64 exec, exec, s[90:91]
	s_cbranch_execz .LBB0_1051
